# lever 4 mirror: static s_setprio 1 for waves 0-3 across every GEMM K loop
# baseline (speedup 1.0000x reference)
.LBB0_74:
	s_lshr_b32 s0, s5, 1
	s_and_b32 s0, s0, 0x1ffff80
	v_or_b32_e32 v0, s0, v154
	s_and_b32 s0, s5, 0xc0
	s_mov_b32 s5, s15
	s_lshl_b64 s[4:5], s[4:5], 16
	v_lshlrev_b32_e32 v128, 7, v0
	v_or_b32_e32 v0, s0, v154
	s_add_u32 s6, s4, s74
	v_lshlrev_b32_e32 v139, 7, v0
	v_lshl_add_u64 v[0:1], s[66:67], 0, v[130:131]
	s_addc_u32 s7, s5, s75
	s_waitcnt vmcnt(16)
	v_lshl_add_u64 v[142:143], v[0:1], 0, s[6:7]
	s_add_u32 s4, s4, s76
	v_lshl_add_u64 v[0:1], s[66:67], 0, v[134:135]
	s_addc_u32 s5, s5, s77
	v_lshl_add_u64 v[146:147], v[0:1], 0, s[6:7]
	v_mov_b32_e32 v0, 0
	v_lshl_add_u64 v[144:145], v[132:133], 0, s[4:5]
	v_lshl_add_u64 v[148:149], v[136:137], 0, s[4:5]
	s_mov_b64 s[4:5], 0
	s_mov_b32 s12, 0
	v_mov_b32_e32 v1, v0
	v_mov_b32_e32 v2, v0
	v_mov_b32_e32 v3, v0
	v_mov_b32_e32 v4, v0
	v_mov_b32_e32 v5, v0
	v_mov_b32_e32 v6, v0
	v_mov_b32_e32 v7, v0
	v_mov_b32_e32 v8, v0
	v_mov_b32_e32 v9, v0
	v_mov_b32_e32 v10, v0
	v_mov_b32_e32 v11, v0
	v_mov_b32_e32 v12, v0
	v_mov_b32_e32 v13, v0
	v_mov_b32_e32 v14, v0
	v_mov_b32_e32 v15, v0
	v_mov_b32_e32 v16, v0
	v_mov_b32_e32 v17, v0
	v_mov_b32_e32 v18, v0
	v_mov_b32_e32 v19, v0
	v_mov_b32_e32 v20, v0
	v_mov_b32_e32 v21, v0
	v_mov_b32_e32 v22, v0
	v_mov_b32_e32 v23, v0
	v_mov_b32_e32 v24, v0
	v_mov_b32_e32 v25, v0
	v_mov_b32_e32 v26, v0
	v_mov_b32_e32 v27, v0
	v_mov_b32_e32 v28, v0
	v_mov_b32_e32 v29, v0
	v_mov_b32_e32 v30, v0
	v_mov_b32_e32 v31, v0
	v_mov_b32_e32 v32, v0
	v_mov_b32_e32 v33, v0
	v_mov_b32_e32 v34, v0
	v_mov_b32_e32 v35, v0
	v_mov_b32_e32 v36, v0
	v_mov_b32_e32 v37, v0
	v_mov_b32_e32 v38, v0
	v_mov_b32_e32 v39, v0
	v_mov_b32_e32 v40, v0
	v_mov_b32_e32 v41, v0
	v_mov_b32_e32 v42, v0
	v_mov_b32_e32 v43, v0
	v_mov_b32_e32 v44, v0
	v_mov_b32_e32 v45, v0
	v_mov_b32_e32 v46, v0
	v_mov_b32_e32 v47, v0
	v_mov_b32_e32 v48, v0
	v_mov_b32_e32 v49, v0
	v_mov_b32_e32 v50, v0
	v_mov_b32_e32 v51, v0
	v_mov_b32_e32 v52, v0
	v_mov_b32_e32 v53, v0
	v_mov_b32_e32 v54, v0
	v_mov_b32_e32 v55, v0
	v_mov_b32_e32 v56, v0
	v_mov_b32_e32 v57, v0
	v_mov_b32_e32 v58, v0
	v_mov_b32_e32 v59, v0
	v_mov_b32_e32 v60, v0
	v_mov_b32_e32 v61, v0
	v_mov_b32_e32 v62, v0
	v_mov_b32_e32 v63, v0
	v_mov_b32_e32 v64, v0
	v_mov_b32_e32 v65, v0
	v_mov_b32_e32 v66, v0
	v_mov_b32_e32 v67, v0
	v_mov_b32_e32 v68, v0
	v_mov_b32_e32 v69, v0
	v_mov_b32_e32 v70, v0
	v_mov_b32_e32 v71, v0
	v_mov_b32_e32 v72, v0
	v_mov_b32_e32 v73, v0
	v_mov_b32_e32 v74, v0
	v_mov_b32_e32 v75, v0
	v_mov_b32_e32 v76, v0
	v_mov_b32_e32 v77, v0
	v_mov_b32_e32 v78, v0
	v_mov_b32_e32 v79, v0
	v_mov_b32_e32 v80, v0
	v_mov_b32_e32 v81, v0
	v_mov_b32_e32 v82, v0
	v_mov_b32_e32 v83, v0
	v_mov_b32_e32 v84, v0
	v_mov_b32_e32 v85, v0
	v_mov_b32_e32 v86, v0
	v_mov_b32_e32 v87, v0
	v_mov_b32_e32 v88, v0
	v_mov_b32_e32 v89, v0
	v_mov_b32_e32 v90, v0
	v_mov_b32_e32 v91, v0
	v_mov_b32_e32 v92, v0
	v_mov_b32_e32 v93, v0
	v_mov_b32_e32 v94, v0
	v_mov_b32_e32 v95, v0
	v_mov_b32_e32 v96, v0
	v_mov_b32_e32 v97, v0
	v_mov_b32_e32 v98, v0
	v_mov_b32_e32 v99, v0
	v_mov_b32_e32 v100, v0
	v_mov_b32_e32 v101, v0
	v_mov_b32_e32 v102, v0
	v_mov_b32_e32 v103, v0
	v_mov_b32_e32 v104, v0
	v_mov_b32_e32 v105, v0
	v_mov_b32_e32 v106, v0
	v_mov_b32_e32 v107, v0
	v_mov_b32_e32 v108, v0
	v_mov_b32_e32 v109, v0
	v_mov_b32_e32 v110, v0
	v_mov_b32_e32 v111, v0
	v_mov_b32_e32 v112, v0
	v_mov_b32_e32 v113, v0
	v_mov_b32_e32 v114, v0
	v_mov_b32_e32 v115, v0
	v_mov_b32_e32 v116, v0
	v_mov_b32_e32 v117, v0
	v_mov_b32_e32 v118, v0
	v_mov_b32_e32 v119, v0
	v_mov_b32_e32 v120, v0
	v_mov_b32_e32 v121, v0
	v_mov_b32_e32 v122, v0
	v_mov_b32_e32 v123, v0
	v_mov_b32_e32 v124, v0
	v_mov_b32_e32 v125, v0
	v_mov_b32_e32 v126, v0
	v_mov_b32_e32 v127, v0
	s_waitcnt vmcnt(16) lgkmcnt(0)
	s_barrier
	v_readfirstlane_b32 s98, v178
	s_nop 3
	s_lshr_b32 s98, s98, 6
	s_cmp_ge_u32 s98, 4
	s_cbranch_scc1 .Lprio_done_1
	s_setprio 1

.LBB0_531:
	s_lshr_b32 s0, s5, 1
	s_and_b32 s0, s0, 0x1ffff80
	v_or_b32_e32 v0, s0, v154
	s_and_b32 s0, s5, 0xc0
	s_mov_b32 s5, s15
	s_lshl_b64 s[4:5], s[4:5], 16
	v_lshlrev_b32_e32 v139, 7, v0
	v_or_b32_e32 v0, s0, v154
	s_add_u32 s12, s4, s74
	v_lshlrev_b32_e32 v128, 7, v0
	v_lshl_add_u64 v[0:1], s[66:67], 0, v[130:131]
	s_addc_u32 s13, s5, s75
	s_waitcnt vmcnt(16)
	v_lshl_add_u64 v[142:143], v[0:1], 0, s[12:13]
	s_add_u32 s6, s4, s76
	v_lshl_add_u64 v[0:1], s[66:67], 0, v[134:135]
	s_addc_u32 s7, s5, s77
	v_lshl_add_u64 v[144:145], v[0:1], 0, s[12:13]
	v_mov_b32_e32 v0, 0
	s_mov_b32 s12, 0
	s_mov_b64 s[4:5], 0
	v_mov_b32_e32 v1, v0
	v_mov_b32_e32 v2, v0
	v_mov_b32_e32 v3, v0
	v_mov_b32_e32 v4, v0
	v_mov_b32_e32 v5, v0
	v_mov_b32_e32 v6, v0
	v_mov_b32_e32 v7, v0
	v_mov_b32_e32 v8, v0
	v_mov_b32_e32 v9, v0
	v_mov_b32_e32 v10, v0
	v_mov_b32_e32 v11, v0
	v_mov_b32_e32 v12, v0
	v_mov_b32_e32 v13, v0
	v_mov_b32_e32 v14, v0
	v_mov_b32_e32 v15, v0
	v_mov_b32_e32 v16, v0
	v_mov_b32_e32 v17, v0
	v_mov_b32_e32 v18, v0
	v_mov_b32_e32 v19, v0
	v_mov_b32_e32 v20, v0
	v_mov_b32_e32 v21, v0
	v_mov_b32_e32 v22, v0
	v_mov_b32_e32 v23, v0
	v_mov_b32_e32 v24, v0
	v_mov_b32_e32 v25, v0
	v_mov_b32_e32 v26, v0
	v_mov_b32_e32 v27, v0
	v_mov_b32_e32 v28, v0
	v_mov_b32_e32 v29, v0
	v_mov_b32_e32 v30, v0
	v_mov_b32_e32 v31, v0
	v_mov_b32_e32 v32, v0
	v_mov_b32_e32 v33, v0
	v_mov_b32_e32 v34, v0
	v_mov_b32_e32 v35, v0
	v_mov_b32_e32 v36, v0
	v_mov_b32_e32 v37, v0
	v_mov_b32_e32 v38, v0
	v_mov_b32_e32 v39, v0
	v_mov_b32_e32 v40, v0
	v_mov_b32_e32 v41, v0
	v_mov_b32_e32 v42, v0
	v_mov_b32_e32 v43, v0
	v_mov_b32_e32 v44, v0
	v_mov_b32_e32 v45, v0
	v_mov_b32_e32 v46, v0
	v_mov_b32_e32 v47, v0
	v_mov_b32_e32 v48, v0
	v_mov_b32_e32 v49, v0
	v_mov_b32_e32 v50, v0
	v_mov_b32_e32 v51, v0
	v_mov_b32_e32 v52, v0
	v_mov_b32_e32 v53, v0
	v_mov_b32_e32 v54, v0
	v_mov_b32_e32 v55, v0
	v_mov_b32_e32 v56, v0
	v_mov_b32_e32 v57, v0
	v_mov_b32_e32 v58, v0
	v_mov_b32_e32 v59, v0
	v_mov_b32_e32 v60, v0
	v_mov_b32_e32 v61, v0
	v_mov_b32_e32 v62, v0
	v_mov_b32_e32 v63, v0
	v_mov_b32_e32 v64, v0
	v_mov_b32_e32 v65, v0
	v_mov_b32_e32 v66, v0
	v_mov_b32_e32 v67, v0
	v_mov_b32_e32 v68, v0
	v_mov_b32_e32 v69, v0
	v_mov_b32_e32 v70, v0
	v_mov_b32_e32 v71, v0
	v_mov_b32_e32 v72, v0
	v_mov_b32_e32 v73, v0
	v_mov_b32_e32 v74, v0
	v_mov_b32_e32 v75, v0
	v_mov_b32_e32 v76, v0
	v_mov_b32_e32 v77, v0
	v_mov_b32_e32 v78, v0
	v_mov_b32_e32 v79, v0
	v_mov_b32_e32 v80, v0
	v_mov_b32_e32 v81, v0
	v_mov_b32_e32 v82, v0
	v_mov_b32_e32 v83, v0
	v_mov_b32_e32 v84, v0
	v_mov_b32_e32 v85, v0
	v_mov_b32_e32 v86, v0
	v_mov_b32_e32 v87, v0
	v_mov_b32_e32 v88, v0
	v_mov_b32_e32 v89, v0
	v_mov_b32_e32 v90, v0
	v_mov_b32_e32 v91, v0
	v_mov_b32_e32 v92, v0
	v_mov_b32_e32 v93, v0
	v_mov_b32_e32 v94, v0
	v_mov_b32_e32 v95, v0
	v_mov_b32_e32 v96, v0
	v_mov_b32_e32 v97, v0
	v_mov_b32_e32 v98, v0
	v_mov_b32_e32 v99, v0
	v_mov_b32_e32 v100, v0
	v_mov_b32_e32 v101, v0
	v_mov_b32_e32 v102, v0
	v_mov_b32_e32 v103, v0
	v_mov_b32_e32 v104, v0
	v_mov_b32_e32 v105, v0
	v_mov_b32_e32 v106, v0
	v_mov_b32_e32 v107, v0
	v_mov_b32_e32 v108, v0
	v_mov_b32_e32 v109, v0
	v_mov_b32_e32 v110, v0
	v_mov_b32_e32 v111, v0
	v_mov_b32_e32 v112, v0
	v_mov_b32_e32 v113, v0
	v_mov_b32_e32 v114, v0
	v_mov_b32_e32 v115, v0
	v_mov_b32_e32 v116, v0
	v_mov_b32_e32 v117, v0
	v_mov_b32_e32 v118, v0
	v_mov_b32_e32 v119, v0
	v_mov_b32_e32 v120, v0
	v_mov_b32_e32 v121, v0
	v_mov_b32_e32 v122, v0
	v_mov_b32_e32 v123, v0
	v_mov_b32_e32 v124, v0
	v_mov_b32_e32 v125, v0
	v_mov_b32_e32 v126, v0
	v_mov_b32_e32 v127, v0
	v_lshl_add_u64 v[146:147], v[132:133], 0, s[6:7]
	v_lshl_add_u64 v[148:149], v[136:137], 0, s[6:7]
	s_waitcnt vmcnt(16) lgkmcnt(0)
	s_barrier
	v_readfirstlane_b32 s98, v178
	s_nop 3
	s_lshr_b32 s98, s98, 6
	s_cmp_ge_u32 s98, 4
	s_cbranch_scc1 .Lprio_done_2
	s_setprio 1

.LBB0_735:
	s_lshr_b32 s38, s37, 1
	s_and_b32 s38, s38, 0x1ffff80
	v_or_b32_e32 v0, s38, v148
	s_and_b32 s37, s37, 0xc0
	v_lshlrev_b32_e32 v139, 7, v0
	v_or_b32_e32 v0, s37, v148
	s_mov_b32 s37, s3
	s_lshl_b64 s[36:37], s[36:37], 16
	s_add_u32 s30, s36, s30
	v_lshlrev_b32_e32 v153, 7, v0
	v_lshl_add_u64 v[0:1], s[28:29], 0, v[130:131]
	s_addc_u32 s31, s37, s31
	s_waitcnt vmcnt(16)
	v_lshl_add_u64 v[140:141], v[0:1], 0, s[30:31]
	s_add_u32 s34, s36, s34
	v_lshl_add_u64 v[0:1], s[28:29], 0, v[134:135]
	s_addc_u32 s35, s37, s35
	v_lshl_add_u64 v[144:145], v[0:1], 0, s[30:31]
	v_mov_b32_e32 v0, 0
	v_lshl_add_u64 v[142:143], v[132:133], 0, s[34:35]
	v_lshl_add_u64 v[146:147], v[136:137], 0, s[34:35]
	s_mov_b64 s[28:29], 0
	s_mov_b32 s34, 0
	v_mov_b32_e32 v1, v0
	v_mov_b32_e32 v2, v0
	v_mov_b32_e32 v3, v0
	v_mov_b32_e32 v4, v0
	v_mov_b32_e32 v5, v0
	v_mov_b32_e32 v6, v0
	v_mov_b32_e32 v7, v0
	v_mov_b32_e32 v8, v0
	v_mov_b32_e32 v9, v0
	v_mov_b32_e32 v10, v0
	v_mov_b32_e32 v11, v0
	v_mov_b32_e32 v12, v0
	v_mov_b32_e32 v13, v0
	v_mov_b32_e32 v14, v0
	v_mov_b32_e32 v15, v0
	v_mov_b32_e32 v16, v0
	v_mov_b32_e32 v17, v0
	v_mov_b32_e32 v18, v0
	v_mov_b32_e32 v19, v0
	v_mov_b32_e32 v20, v0
	v_mov_b32_e32 v21, v0
	v_mov_b32_e32 v22, v0
	v_mov_b32_e32 v23, v0
	v_mov_b32_e32 v24, v0
	v_mov_b32_e32 v25, v0
	v_mov_b32_e32 v26, v0
	v_mov_b32_e32 v27, v0
	v_mov_b32_e32 v28, v0
	v_mov_b32_e32 v29, v0
	v_mov_b32_e32 v30, v0
	v_mov_b32_e32 v31, v0
	v_mov_b32_e32 v32, v0
	v_mov_b32_e32 v33, v0
	v_mov_b32_e32 v34, v0
	v_mov_b32_e32 v35, v0
	v_mov_b32_e32 v36, v0
	v_mov_b32_e32 v37, v0
	v_mov_b32_e32 v38, v0
	v_mov_b32_e32 v39, v0
	v_mov_b32_e32 v40, v0
	v_mov_b32_e32 v41, v0
	v_mov_b32_e32 v42, v0
	v_mov_b32_e32 v43, v0
	v_mov_b32_e32 v44, v0
	v_mov_b32_e32 v45, v0
	v_mov_b32_e32 v46, v0
	v_mov_b32_e32 v47, v0
	v_mov_b32_e32 v48, v0
	v_mov_b32_e32 v49, v0
	v_mov_b32_e32 v50, v0
	v_mov_b32_e32 v51, v0
	v_mov_b32_e32 v52, v0
	v_mov_b32_e32 v53, v0
	v_mov_b32_e32 v54, v0
	v_mov_b32_e32 v55, v0
	v_mov_b32_e32 v56, v0
	v_mov_b32_e32 v57, v0
	v_mov_b32_e32 v58, v0
	v_mov_b32_e32 v59, v0
	v_mov_b32_e32 v60, v0
	v_mov_b32_e32 v61, v0
	v_mov_b32_e32 v62, v0
	v_mov_b32_e32 v63, v0
	v_mov_b32_e32 v64, v0
	v_mov_b32_e32 v65, v0
	v_mov_b32_e32 v66, v0
	v_mov_b32_e32 v67, v0
	v_mov_b32_e32 v68, v0
	v_mov_b32_e32 v69, v0
	v_mov_b32_e32 v70, v0
	v_mov_b32_e32 v71, v0
	v_mov_b32_e32 v72, v0
	v_mov_b32_e32 v73, v0
	v_mov_b32_e32 v74, v0
	v_mov_b32_e32 v75, v0
	v_mov_b32_e32 v76, v0
	v_mov_b32_e32 v77, v0
	v_mov_b32_e32 v78, v0
	v_mov_b32_e32 v79, v0
	v_mov_b32_e32 v80, v0
	v_mov_b32_e32 v81, v0
	v_mov_b32_e32 v82, v0
	v_mov_b32_e32 v83, v0
	v_mov_b32_e32 v84, v0
	v_mov_b32_e32 v85, v0
	v_mov_b32_e32 v86, v0
	v_mov_b32_e32 v87, v0
	v_mov_b32_e32 v88, v0
	v_mov_b32_e32 v89, v0
	v_mov_b32_e32 v90, v0
	v_mov_b32_e32 v91, v0
	v_mov_b32_e32 v92, v0
	v_mov_b32_e32 v93, v0
	v_mov_b32_e32 v94, v0
	v_mov_b32_e32 v95, v0
	v_mov_b32_e32 v96, v0
	v_mov_b32_e32 v97, v0
	v_mov_b32_e32 v98, v0
	v_mov_b32_e32 v99, v0
	v_mov_b32_e32 v100, v0
	v_mov_b32_e32 v101, v0
	v_mov_b32_e32 v102, v0
	v_mov_b32_e32 v103, v0
	v_mov_b32_e32 v104, v0
	v_mov_b32_e32 v105, v0
	v_mov_b32_e32 v106, v0
	v_mov_b32_e32 v107, v0
	v_mov_b32_e32 v108, v0
	v_mov_b32_e32 v109, v0
	v_mov_b32_e32 v110, v0
	v_mov_b32_e32 v111, v0
	v_mov_b32_e32 v112, v0
	v_mov_b32_e32 v113, v0
	v_mov_b32_e32 v114, v0
	v_mov_b32_e32 v115, v0
	v_mov_b32_e32 v116, v0
	v_mov_b32_e32 v117, v0
	v_mov_b32_e32 v118, v0
	v_mov_b32_e32 v119, v0
	v_mov_b32_e32 v120, v0
	v_mov_b32_e32 v121, v0
	v_mov_b32_e32 v122, v0
	v_mov_b32_e32 v123, v0
	v_mov_b32_e32 v124, v0
	v_mov_b32_e32 v125, v0
	v_mov_b32_e32 v126, v0
	v_mov_b32_e32 v127, v0
	s_waitcnt vmcnt(16) lgkmcnt(0)
	s_barrier
	v_readfirstlane_b32 s98, v178
	s_nop 3
	s_lshr_b32 s98, s98, 6
	s_cmp_ge_u32 s98, 4
	s_cbranch_scc1 .Lprio_done_3
	s_setprio 1

.LBB0_791:
	s_lshr_b32 s46, s45, 1
	s_and_b32 s46, s46, 0x1ffff80
	v_or_b32_e32 v0, s46, v148
	s_and_b32 s45, s45, 0xc0
	v_lshlrev_b32_e32 v139, 7, v0
	v_or_b32_e32 v0, s45, v148
	s_mov_b32 s45, s11
	s_lshl_b64 s[44:45], s[44:45], 16
	s_add_u32 s40, s44, s40
	s_addc_u32 s41, s45, s41
	s_waitcnt vmcnt(16)
	v_lshlrev_b32_e32 v153, 7, v0
	v_lshl_add_u64 v[0:1], s[38:39], 0, v[130:131]
	s_add_u32 s42, s44, s42
	v_lshl_add_u64 v[140:141], v[0:1], 0, s[40:41]
	s_addc_u32 s43, s45, s43
	v_lshl_add_u64 v[0:1], s[38:39], 0, v[134:135]
	v_mov_b32_e32 v88, 0
	v_lshl_add_u64 v[142:143], v[132:133], 0, s[42:43]
	v_lshl_add_u64 v[144:145], v[0:1], 0, s[40:41]
	v_lshl_add_u64 v[146:147], v[136:137], 0, s[42:43]
	s_mov_b64 s[38:39], 0
	s_mov_b32 s40, 0
	v_mov_b32_e32 v89, v88
	v_mov_b32_e32 v90, v88
	v_mov_b32_e32 v91, v88
	v_mov_b32_e32 v104, v88
	v_mov_b32_e32 v105, v88
	v_mov_b32_e32 v106, v88
	v_mov_b32_e32 v107, v88
	v_mov_b32_e32 v0, v88
	v_mov_b32_e32 v1, v88
	v_mov_b32_e32 v2, v88
	v_mov_b32_e32 v3, v88
	v_mov_b32_e32 v4, v88
	v_mov_b32_e32 v5, v88
	v_mov_b32_e32 v6, v88
	v_mov_b32_e32 v7, v88
	v_mov_b32_e32 v8, v88
	v_mov_b32_e32 v9, v88
	v_mov_b32_e32 v10, v88
	v_mov_b32_e32 v11, v88
	v_mov_b32_e32 v12, v88
	v_mov_b32_e32 v13, v88
	v_mov_b32_e32 v14, v88
	v_mov_b32_e32 v15, v88
	v_mov_b32_e32 v16, v88
	v_mov_b32_e32 v17, v88
	v_mov_b32_e32 v18, v88
	v_mov_b32_e32 v19, v88
	v_mov_b32_e32 v20, v88
	v_mov_b32_e32 v21, v88
	v_mov_b32_e32 v22, v88
	v_mov_b32_e32 v23, v88
	v_mov_b32_e32 v24, v88
	v_mov_b32_e32 v25, v88
	v_mov_b32_e32 v26, v88
	v_mov_b32_e32 v27, v88
	v_mov_b32_e32 v28, v88
	v_mov_b32_e32 v29, v88
	v_mov_b32_e32 v30, v88
	v_mov_b32_e32 v31, v88
	v_mov_b32_e32 v32, v88
	v_mov_b32_e32 v33, v88
	v_mov_b32_e32 v34, v88
	v_mov_b32_e32 v35, v88
	v_mov_b32_e32 v36, v88
	v_mov_b32_e32 v37, v88
	v_mov_b32_e32 v38, v88
	v_mov_b32_e32 v39, v88
	v_mov_b32_e32 v40, v88
	v_mov_b32_e32 v41, v88
	v_mov_b32_e32 v42, v88
	v_mov_b32_e32 v43, v88
	v_mov_b32_e32 v44, v88
	v_mov_b32_e32 v45, v88
	v_mov_b32_e32 v46, v88
	v_mov_b32_e32 v47, v88
	v_mov_b32_e32 v48, v88
	v_mov_b32_e32 v49, v88
	v_mov_b32_e32 v50, v88
	v_mov_b32_e32 v51, v88
	v_mov_b32_e32 v52, v88
	v_mov_b32_e32 v53, v88
	v_mov_b32_e32 v54, v88
	v_mov_b32_e32 v55, v88
	v_mov_b32_e32 v56, v88
	v_mov_b32_e32 v57, v88
	v_mov_b32_e32 v58, v88
	v_mov_b32_e32 v59, v88
	v_mov_b32_e32 v60, v88
	v_mov_b32_e32 v61, v88
	v_mov_b32_e32 v62, v88
	v_mov_b32_e32 v63, v88
	v_mov_b32_e32 v64, v88
	v_mov_b32_e32 v65, v88
	v_mov_b32_e32 v66, v88
	v_mov_b32_e32 v67, v88
	v_mov_b32_e32 v68, v88
	v_mov_b32_e32 v69, v88
	v_mov_b32_e32 v70, v88
	v_mov_b32_e32 v71, v88
	v_mov_b32_e32 v72, v88
	v_mov_b32_e32 v73, v88
	v_mov_b32_e32 v74, v88
	v_mov_b32_e32 v75, v88
	v_mov_b32_e32 v76, v88
	v_mov_b32_e32 v77, v88
	v_mov_b32_e32 v78, v88
	v_mov_b32_e32 v79, v88
	v_mov_b32_e32 v80, v88
	v_mov_b32_e32 v81, v88
	v_mov_b32_e32 v82, v88
	v_mov_b32_e32 v83, v88
	v_mov_b32_e32 v84, v88
	v_mov_b32_e32 v85, v88
	v_mov_b32_e32 v86, v88
	v_mov_b32_e32 v87, v88
	v_mov_b32_e32 v92, v88
	v_mov_b32_e32 v93, v88
	v_mov_b32_e32 v94, v88
	v_mov_b32_e32 v95, v88
	v_mov_b32_e32 v96, v88
	v_mov_b32_e32 v97, v88
	v_mov_b32_e32 v98, v88
	v_mov_b32_e32 v99, v88
	v_mov_b32_e32 v100, v88
	v_mov_b32_e32 v101, v88
	v_mov_b32_e32 v102, v88
	v_mov_b32_e32 v103, v88
	v_mov_b32_e32 v108, v88
	v_mov_b32_e32 v109, v88
	v_mov_b32_e32 v110, v88
	v_mov_b32_e32 v111, v88
	v_mov_b32_e32 v112, v88
	v_mov_b32_e32 v113, v88
	v_mov_b32_e32 v114, v88
	v_mov_b32_e32 v115, v88
	v_mov_b32_e32 v116, v88
	v_mov_b32_e32 v117, v88
	v_mov_b32_e32 v118, v88
	v_mov_b32_e32 v119, v88
	v_mov_b32_e32 v120, v88
	v_mov_b32_e32 v121, v88
	v_mov_b32_e32 v122, v88
	v_mov_b32_e32 v123, v88
	v_mov_b32_e32 v124, v88
	v_mov_b32_e32 v125, v88
	v_mov_b32_e32 v126, v88
	v_mov_b32_e32 v127, v88
	s_waitcnt vmcnt(16) lgkmcnt(0)
	s_barrier
	v_readfirstlane_b32 s98, v178
	s_nop 3
	s_lshr_b32 s98, s98, 6
	s_cmp_ge_u32 s98, 4
	s_cbranch_scc1 .Lprio_done_4
	s_setprio 1

.LBB0_1139:
	s_lshr_b32 s48, s47, 1
	s_and_b32 s48, s48, 0x1ffff80
	v_or_b32_e32 v0, s48, v148
	s_and_b32 s47, s47, 0xc0
	v_lshlrev_b32_e32 v139, 7, v0
	v_or_b32_e32 v0, s47, v148
	s_mov_b32 s47, s3
	s_lshl_b64 s[46:47], s[46:47], 16
	s_add_u32 s42, s46, s42
	s_addc_u32 s43, s47, s43
	s_waitcnt vmcnt(16)
	v_lshlrev_b32_e32 v153, 7, v0
	v_lshl_add_u64 v[0:1], s[40:41], 0, v[130:131]
	s_add_u32 s44, s46, s44
	v_lshl_add_u64 v[140:141], v[0:1], 0, s[42:43]
	s_addc_u32 s45, s47, s45
	v_lshl_add_u64 v[0:1], s[40:41], 0, v[134:135]
	v_mov_b32_e32 v88, 0
	v_lshl_add_u64 v[142:143], v[132:133], 0, s[44:45]
	v_lshl_add_u64 v[144:145], v[0:1], 0, s[42:43]
	v_lshl_add_u64 v[146:147], v[136:137], 0, s[44:45]
	s_mov_b64 s[40:41], 0
	s_mov_b32 s42, 0
	v_mov_b32_e32 v89, v88
	v_mov_b32_e32 v90, v88
	v_mov_b32_e32 v91, v88
	v_mov_b32_e32 v104, v88
	v_mov_b32_e32 v105, v88
	v_mov_b32_e32 v106, v88
	v_mov_b32_e32 v107, v88
	v_mov_b32_e32 v0, v88
	v_mov_b32_e32 v1, v88
	v_mov_b32_e32 v2, v88
	v_mov_b32_e32 v3, v88
	v_mov_b32_e32 v4, v88
	v_mov_b32_e32 v5, v88
	v_mov_b32_e32 v6, v88
	v_mov_b32_e32 v7, v88
	v_mov_b32_e32 v8, v88
	v_mov_b32_e32 v9, v88
	v_mov_b32_e32 v10, v88
	v_mov_b32_e32 v11, v88
	v_mov_b32_e32 v12, v88
	v_mov_b32_e32 v13, v88
	v_mov_b32_e32 v14, v88
	v_mov_b32_e32 v15, v88
	v_mov_b32_e32 v16, v88
	v_mov_b32_e32 v17, v88
	v_mov_b32_e32 v18, v88
	v_mov_b32_e32 v19, v88
	v_mov_b32_e32 v20, v88
	v_mov_b32_e32 v21, v88
	v_mov_b32_e32 v22, v88
	v_mov_b32_e32 v23, v88
	v_mov_b32_e32 v24, v88
	v_mov_b32_e32 v25, v88
	v_mov_b32_e32 v26, v88
	v_mov_b32_e32 v27, v88
	v_mov_b32_e32 v28, v88
	v_mov_b32_e32 v29, v88
	v_mov_b32_e32 v30, v88
	v_mov_b32_e32 v31, v88
	v_mov_b32_e32 v32, v88
	v_mov_b32_e32 v33, v88
	v_mov_b32_e32 v34, v88
	v_mov_b32_e32 v35, v88
	v_mov_b32_e32 v36, v88
	v_mov_b32_e32 v37, v88
	v_mov_b32_e32 v38, v88
	v_mov_b32_e32 v39, v88
	v_mov_b32_e32 v40, v88
	v_mov_b32_e32 v41, v88
	v_mov_b32_e32 v42, v88
	v_mov_b32_e32 v43, v88
	v_mov_b32_e32 v44, v88
	v_mov_b32_e32 v45, v88
	v_mov_b32_e32 v46, v88
	v_mov_b32_e32 v47, v88
	v_mov_b32_e32 v48, v88
	v_mov_b32_e32 v49, v88
	v_mov_b32_e32 v50, v88
	v_mov_b32_e32 v51, v88
	v_mov_b32_e32 v52, v88
	v_mov_b32_e32 v53, v88
	v_mov_b32_e32 v54, v88
	v_mov_b32_e32 v55, v88
	v_mov_b32_e32 v56, v88
	v_mov_b32_e32 v57, v88
	v_mov_b32_e32 v58, v88
	v_mov_b32_e32 v59, v88
	v_mov_b32_e32 v60, v88
	v_mov_b32_e32 v61, v88
	v_mov_b32_e32 v62, v88
	v_mov_b32_e32 v63, v88
	v_mov_b32_e32 v64, v88
	v_mov_b32_e32 v65, v88
	v_mov_b32_e32 v66, v88
	v_mov_b32_e32 v67, v88
	v_mov_b32_e32 v68, v88
	v_mov_b32_e32 v69, v88
	v_mov_b32_e32 v70, v88
	v_mov_b32_e32 v71, v88
	v_mov_b32_e32 v72, v88
	v_mov_b32_e32 v73, v88
	v_mov_b32_e32 v74, v88
	v_mov_b32_e32 v75, v88
	v_mov_b32_e32 v76, v88
	v_mov_b32_e32 v77, v88
	v_mov_b32_e32 v78, v88
	v_mov_b32_e32 v79, v88
	v_mov_b32_e32 v80, v88
	v_mov_b32_e32 v81, v88
	v_mov_b32_e32 v82, v88
	v_mov_b32_e32 v83, v88
	v_mov_b32_e32 v84, v88
	v_mov_b32_e32 v85, v88
	v_mov_b32_e32 v86, v88
	v_mov_b32_e32 v87, v88
	v_mov_b32_e32 v92, v88
	v_mov_b32_e32 v93, v88
	v_mov_b32_e32 v94, v88
	v_mov_b32_e32 v95, v88
	v_mov_b32_e32 v96, v88
	v_mov_b32_e32 v97, v88
	v_mov_b32_e32 v98, v88
	v_mov_b32_e32 v99, v88
	v_mov_b32_e32 v100, v88
	v_mov_b32_e32 v101, v88
	v_mov_b32_e32 v102, v88
	v_mov_b32_e32 v103, v88
	v_mov_b32_e32 v108, v88
	v_mov_b32_e32 v109, v88
	v_mov_b32_e32 v110, v88
	v_mov_b32_e32 v111, v88
	v_mov_b32_e32 v112, v88
	v_mov_b32_e32 v113, v88
	v_mov_b32_e32 v114, v88
	v_mov_b32_e32 v115, v88
	v_mov_b32_e32 v116, v88
	v_mov_b32_e32 v117, v88
	v_mov_b32_e32 v118, v88
	v_mov_b32_e32 v119, v88
	v_mov_b32_e32 v120, v88
	v_mov_b32_e32 v121, v88
	v_mov_b32_e32 v122, v88
	v_mov_b32_e32 v123, v88
	v_mov_b32_e32 v124, v88
	v_mov_b32_e32 v125, v88
	v_mov_b32_e32 v126, v88
	v_mov_b32_e32 v127, v88
	s_waitcnt vmcnt(16) lgkmcnt(0)
	s_barrier
	v_readfirstlane_b32 s98, v178
	s_nop 3
	s_lshr_b32 s98, s98, 6
	s_cmp_ge_u32 s98, 4
	s_cbranch_scc1 .Lprio_done_5
	s_setprio 1

.LBB0_1186:
	s_lshr_b32 s50, s49, 1
	s_and_b32 s50, s50, 0x1ffff80
	v_or_b32_e32 v0, s50, v148
	s_and_b32 s49, s49, 0xc0
	v_lshlrev_b32_e32 v139, 7, v0
	v_or_b32_e32 v0, s49, v148
	s_mov_b32 s49, s3
	s_lshl_b64 s[48:49], s[48:49], 17
	s_add_u32 s44, s48, s44
	s_addc_u32 s45, s49, s45
	s_waitcnt vmcnt(16)
	v_lshlrev_b32_e32 v153, 7, v0
	v_lshl_add_u64 v[0:1], s[42:43], 0, v[130:131]
	s_add_u32 s46, s48, s46
	v_lshl_add_u64 v[140:141], v[0:1], 0, s[44:45]
	s_addc_u32 s47, s49, s47
	v_lshl_add_u64 v[0:1], s[42:43], 0, v[134:135]
	v_mov_b32_e32 v88, 0
	v_lshl_add_u64 v[142:143], v[132:133], 0, s[46:47]
	v_lshl_add_u64 v[144:145], v[0:1], 0, s[44:45]
	v_lshl_add_u64 v[146:147], v[136:137], 0, s[46:47]
	s_mov_b64 s[42:43], 0
	s_mov_b32 s44, 0
	v_mov_b32_e32 v89, v88
	v_mov_b32_e32 v90, v88
	v_mov_b32_e32 v91, v88
	v_mov_b32_e32 v104, v88
	v_mov_b32_e32 v105, v88
	v_mov_b32_e32 v106, v88
	v_mov_b32_e32 v107, v88
	v_mov_b32_e32 v0, v88
	v_mov_b32_e32 v1, v88
	v_mov_b32_e32 v2, v88
	v_mov_b32_e32 v3, v88
	v_mov_b32_e32 v4, v88
	v_mov_b32_e32 v5, v88
	v_mov_b32_e32 v6, v88
	v_mov_b32_e32 v7, v88
	v_mov_b32_e32 v8, v88
	v_mov_b32_e32 v9, v88
	v_mov_b32_e32 v10, v88
	v_mov_b32_e32 v11, v88
	v_mov_b32_e32 v12, v88
	v_mov_b32_e32 v13, v88
	v_mov_b32_e32 v14, v88
	v_mov_b32_e32 v15, v88
	v_mov_b32_e32 v16, v88
	v_mov_b32_e32 v17, v88
	v_mov_b32_e32 v18, v88
	v_mov_b32_e32 v19, v88
	v_mov_b32_e32 v20, v88
	v_mov_b32_e32 v21, v88
	v_mov_b32_e32 v22, v88
	v_mov_b32_e32 v23, v88
	v_mov_b32_e32 v24, v88
	v_mov_b32_e32 v25, v88
	v_mov_b32_e32 v26, v88
	v_mov_b32_e32 v27, v88
	v_mov_b32_e32 v28, v88
	v_mov_b32_e32 v29, v88
	v_mov_b32_e32 v30, v88
	v_mov_b32_e32 v31, v88
	v_mov_b32_e32 v32, v88
	v_mov_b32_e32 v33, v88
	v_mov_b32_e32 v34, v88
	v_mov_b32_e32 v35, v88
	v_mov_b32_e32 v36, v88
	v_mov_b32_e32 v37, v88
	v_mov_b32_e32 v38, v88
	v_mov_b32_e32 v39, v88
	v_mov_b32_e32 v40, v88
	v_mov_b32_e32 v41, v88
	v_mov_b32_e32 v42, v88
	v_mov_b32_e32 v43, v88
	v_mov_b32_e32 v44, v88
	v_mov_b32_e32 v45, v88
	v_mov_b32_e32 v46, v88
	v_mov_b32_e32 v47, v88
	v_mov_b32_e32 v48, v88
	v_mov_b32_e32 v49, v88
	v_mov_b32_e32 v50, v88
	v_mov_b32_e32 v51, v88
	v_mov_b32_e32 v52, v88
	v_mov_b32_e32 v53, v88
	v_mov_b32_e32 v54, v88
	v_mov_b32_e32 v55, v88
	v_mov_b32_e32 v56, v88
	v_mov_b32_e32 v57, v88
	v_mov_b32_e32 v58, v88
	v_mov_b32_e32 v59, v88
	v_mov_b32_e32 v60, v88
	v_mov_b32_e32 v61, v88
	v_mov_b32_e32 v62, v88
	v_mov_b32_e32 v63, v88
	v_mov_b32_e32 v64, v88
	v_mov_b32_e32 v65, v88
	v_mov_b32_e32 v66, v88
	v_mov_b32_e32 v67, v88
	v_mov_b32_e32 v68, v88
	v_mov_b32_e32 v69, v88
	v_mov_b32_e32 v70, v88
	v_mov_b32_e32 v71, v88
	v_mov_b32_e32 v72, v88
	v_mov_b32_e32 v73, v88
	v_mov_b32_e32 v74, v88
	v_mov_b32_e32 v75, v88
	v_mov_b32_e32 v76, v88
	v_mov_b32_e32 v77, v88
	v_mov_b32_e32 v78, v88
	v_mov_b32_e32 v79, v88
	v_mov_b32_e32 v80, v88
	v_mov_b32_e32 v81, v88
	v_mov_b32_e32 v82, v88
	v_mov_b32_e32 v83, v88
	v_mov_b32_e32 v84, v88
	v_mov_b32_e32 v85, v88
	v_mov_b32_e32 v86, v88
	v_mov_b32_e32 v87, v88
	v_mov_b32_e32 v92, v88
	v_mov_b32_e32 v93, v88
	v_mov_b32_e32 v94, v88
	v_mov_b32_e32 v95, v88
	v_mov_b32_e32 v96, v88
	v_mov_b32_e32 v97, v88
	v_mov_b32_e32 v98, v88
	v_mov_b32_e32 v99, v88
	v_mov_b32_e32 v100, v88
	v_mov_b32_e32 v101, v88
	v_mov_b32_e32 v102, v88
	v_mov_b32_e32 v103, v88
	v_mov_b32_e32 v108, v88
	v_mov_b32_e32 v109, v88
	v_mov_b32_e32 v110, v88
	v_mov_b32_e32 v111, v88
	v_mov_b32_e32 v112, v88
	v_mov_b32_e32 v113, v88
	v_mov_b32_e32 v114, v88
	v_mov_b32_e32 v115, v88
	v_mov_b32_e32 v116, v88
	v_mov_b32_e32 v117, v88
	v_mov_b32_e32 v118, v88
	v_mov_b32_e32 v119, v88
	v_mov_b32_e32 v120, v88
	v_mov_b32_e32 v121, v88
	v_mov_b32_e32 v122, v88
	v_mov_b32_e32 v123, v88
	v_mov_b32_e32 v124, v88
	v_mov_b32_e32 v125, v88
	v_mov_b32_e32 v126, v88
	v_mov_b32_e32 v127, v88
	s_waitcnt vmcnt(16) lgkmcnt(0)
	s_barrier
	v_readfirstlane_b32 s98, v178
	s_nop 3
	s_lshr_b32 s98, s98, 6
	s_cmp_ge_u32 s98, 4
	s_cbranch_scc1 .Lprio_done_6
	s_setprio 1

.LBB0_1242:
	s_lshr_b32 s48, s47, 1
	s_and_b32 s48, s48, 0x1ffff80
	v_or_b32_e32 v0, s48, v150
	s_and_b32 s47, s47, 0xc0
	v_lshlrev_b32_e32 v128, 7, v0
	v_or_b32_e32 v0, s47, v150
	s_mov_b32 s47, s11
	s_lshl_b64 s[46:47], s[46:47], 16
	s_add_u32 s42, s46, s42
	s_addc_u32 s43, s47, s43
	s_waitcnt vmcnt(16)
	v_lshlrev_b32_e32 v139, 7, v0
	v_lshl_add_u64 v[0:1], s[40:41], 0, v[130:131]
	s_add_u32 s44, s46, s44
	v_lshl_add_u64 v[142:143], v[0:1], 0, s[42:43]
	s_addc_u32 s45, s47, s45
	v_lshl_add_u64 v[0:1], s[40:41], 0, v[134:135]
	v_mov_b32_e32 v88, 0
	v_lshl_add_u64 v[144:145], v[132:133], 0, s[44:45]
	v_lshl_add_u64 v[146:147], v[0:1], 0, s[42:43]
	v_lshl_add_u64 v[148:149], v[136:137], 0, s[44:45]
	s_mov_b64 s[40:41], 0
	s_mov_b32 s42, 0
	v_mov_b32_e32 v89, v88
	v_mov_b32_e32 v90, v88
	v_mov_b32_e32 v91, v88
	v_mov_b32_e32 v104, v88
	v_mov_b32_e32 v105, v88
	v_mov_b32_e32 v106, v88
	v_mov_b32_e32 v107, v88
	v_mov_b32_e32 v0, v88
	v_mov_b32_e32 v1, v88
	v_mov_b32_e32 v2, v88
	v_mov_b32_e32 v3, v88
	v_mov_b32_e32 v4, v88
	v_mov_b32_e32 v5, v88
	v_mov_b32_e32 v6, v88
	v_mov_b32_e32 v7, v88
	v_mov_b32_e32 v8, v88
	v_mov_b32_e32 v9, v88
	v_mov_b32_e32 v10, v88
	v_mov_b32_e32 v11, v88
	v_mov_b32_e32 v12, v88
	v_mov_b32_e32 v13, v88
	v_mov_b32_e32 v14, v88
	v_mov_b32_e32 v15, v88
	v_mov_b32_e32 v16, v88
	v_mov_b32_e32 v17, v88
	v_mov_b32_e32 v18, v88
	v_mov_b32_e32 v19, v88
	v_mov_b32_e32 v20, v88
	v_mov_b32_e32 v21, v88
	v_mov_b32_e32 v22, v88
	v_mov_b32_e32 v23, v88
	v_mov_b32_e32 v24, v88
	v_mov_b32_e32 v25, v88
	v_mov_b32_e32 v26, v88
	v_mov_b32_e32 v27, v88
	v_mov_b32_e32 v28, v88
	v_mov_b32_e32 v29, v88
	v_mov_b32_e32 v30, v88
	v_mov_b32_e32 v31, v88
	v_mov_b32_e32 v32, v88
	v_mov_b32_e32 v33, v88
	v_mov_b32_e32 v34, v88
	v_mov_b32_e32 v35, v88
	v_mov_b32_e32 v36, v88
	v_mov_b32_e32 v37, v88
	v_mov_b32_e32 v38, v88
	v_mov_b32_e32 v39, v88
	v_mov_b32_e32 v40, v88
	v_mov_b32_e32 v41, v88
	v_mov_b32_e32 v42, v88
	v_mov_b32_e32 v43, v88
	v_mov_b32_e32 v44, v88
	v_mov_b32_e32 v45, v88
	v_mov_b32_e32 v46, v88
	v_mov_b32_e32 v47, v88
	v_mov_b32_e32 v48, v88
	v_mov_b32_e32 v49, v88
	v_mov_b32_e32 v50, v88
	v_mov_b32_e32 v51, v88
	v_mov_b32_e32 v52, v88
	v_mov_b32_e32 v53, v88
	v_mov_b32_e32 v54, v88
	v_mov_b32_e32 v55, v88
	v_mov_b32_e32 v56, v88
	v_mov_b32_e32 v57, v88
	v_mov_b32_e32 v58, v88
	v_mov_b32_e32 v59, v88
	v_mov_b32_e32 v60, v88
	v_mov_b32_e32 v61, v88
	v_mov_b32_e32 v62, v88
	v_mov_b32_e32 v63, v88
	v_mov_b32_e32 v64, v88
	v_mov_b32_e32 v65, v88
	v_mov_b32_e32 v66, v88
	v_mov_b32_e32 v67, v88
	v_mov_b32_e32 v68, v88
	v_mov_b32_e32 v69, v88
	v_mov_b32_e32 v70, v88
	v_mov_b32_e32 v71, v88
	v_mov_b32_e32 v72, v88
	v_mov_b32_e32 v73, v88
	v_mov_b32_e32 v74, v88
	v_mov_b32_e32 v75, v88
	v_mov_b32_e32 v76, v88
	v_mov_b32_e32 v77, v88
	v_mov_b32_e32 v78, v88
	v_mov_b32_e32 v79, v88
	v_mov_b32_e32 v80, v88
	v_mov_b32_e32 v81, v88
	v_mov_b32_e32 v82, v88
	v_mov_b32_e32 v83, v88
	v_mov_b32_e32 v84, v88
	v_mov_b32_e32 v85, v88
	v_mov_b32_e32 v86, v88
	v_mov_b32_e32 v87, v88
	v_mov_b32_e32 v92, v88
	v_mov_b32_e32 v93, v88
	v_mov_b32_e32 v94, v88
	v_mov_b32_e32 v95, v88
	v_mov_b32_e32 v96, v88
	v_mov_b32_e32 v97, v88
	v_mov_b32_e32 v98, v88
	v_mov_b32_e32 v99, v88
	v_mov_b32_e32 v100, v88
	v_mov_b32_e32 v101, v88
	v_mov_b32_e32 v102, v88
	v_mov_b32_e32 v103, v88
	v_mov_b32_e32 v108, v88
	v_mov_b32_e32 v109, v88
	v_mov_b32_e32 v110, v88
	v_mov_b32_e32 v111, v88
	v_mov_b32_e32 v112, v88
	v_mov_b32_e32 v113, v88
	v_mov_b32_e32 v114, v88
	v_mov_b32_e32 v115, v88
	v_mov_b32_e32 v116, v88
	v_mov_b32_e32 v117, v88
	v_mov_b32_e32 v118, v88
	v_mov_b32_e32 v119, v88
	v_mov_b32_e32 v120, v88
	v_mov_b32_e32 v121, v88
	v_mov_b32_e32 v122, v88
	v_mov_b32_e32 v123, v88
	v_mov_b32_e32 v124, v88
	v_mov_b32_e32 v125, v88
	v_mov_b32_e32 v126, v88
	v_mov_b32_e32 v127, v88
	s_waitcnt vmcnt(16) lgkmcnt(0)
	s_barrier
	v_readfirstlane_b32 s98, v178
	s_nop 3
	s_lshr_b32 s98, s98, 6
	s_cmp_ge_u32 s98, 4
	s_cbranch_scc1 .Lprio_done_7
	s_setprio 1

.LBB0_1613:
	s_lshr_b32 s4, s3, 1
	s_and_b32 s4, s4, 0x1ffff80
	v_or_b32_e32 v0, s4, v154
	s_and_b32 s3, s3, 0xc0
	v_lshlrev_b32_e32 v128, 7, v0
	v_or_b32_e32 v0, s3, v154
	s_mov_b32 s3, s15
	s_lshl_b64 s[2:3], s[2:3], 16
	s_add_u32 s4, s2, s74
	v_lshlrev_b32_e32 v139, 7, v0
	v_lshl_add_u64 v[0:1], s[66:67], 0, v[130:131]
	s_addc_u32 s5, s3, s75
	s_waitcnt vmcnt(16)
	v_lshl_add_u64 v[142:143], v[0:1], 0, s[4:5]
	s_add_u32 s2, s2, s76
	v_lshl_add_u64 v[0:1], s[66:67], 0, v[134:135]
	s_addc_u32 s3, s3, s77
	v_lshl_add_u64 v[146:147], v[0:1], 0, s[4:5]
	v_mov_b32_e32 v0, 0
	v_lshl_add_u64 v[144:145], v[132:133], 0, s[2:3]
	v_lshl_add_u64 v[148:149], v[136:137], 0, s[2:3]
	s_mov_b64 s[2:3], 0
	s_mov_b32 s10, 0
	v_mov_b32_e32 v1, v0
	v_mov_b32_e32 v2, v0
	v_mov_b32_e32 v3, v0
	v_mov_b32_e32 v4, v0
	v_mov_b32_e32 v5, v0
	v_mov_b32_e32 v6, v0
	v_mov_b32_e32 v7, v0
	v_mov_b32_e32 v8, v0
	v_mov_b32_e32 v9, v0
	v_mov_b32_e32 v10, v0
	v_mov_b32_e32 v11, v0
	v_mov_b32_e32 v12, v0
	v_mov_b32_e32 v13, v0
	v_mov_b32_e32 v14, v0
	v_mov_b32_e32 v15, v0
	v_mov_b32_e32 v16, v0
	v_mov_b32_e32 v17, v0
	v_mov_b32_e32 v18, v0
	v_mov_b32_e32 v19, v0
	v_mov_b32_e32 v20, v0
	v_mov_b32_e32 v21, v0
	v_mov_b32_e32 v22, v0
	v_mov_b32_e32 v23, v0
	v_mov_b32_e32 v24, v0
	v_mov_b32_e32 v25, v0
	v_mov_b32_e32 v26, v0
	v_mov_b32_e32 v27, v0
	v_mov_b32_e32 v28, v0
	v_mov_b32_e32 v29, v0
	v_mov_b32_e32 v30, v0
	v_mov_b32_e32 v31, v0
	v_mov_b32_e32 v32, v0
	v_mov_b32_e32 v33, v0
	v_mov_b32_e32 v34, v0
	v_mov_b32_e32 v35, v0
	v_mov_b32_e32 v36, v0
	v_mov_b32_e32 v37, v0
	v_mov_b32_e32 v38, v0
	v_mov_b32_e32 v39, v0
	v_mov_b32_e32 v40, v0
	v_mov_b32_e32 v41, v0
	v_mov_b32_e32 v42, v0
	v_mov_b32_e32 v43, v0
	v_mov_b32_e32 v44, v0
	v_mov_b32_e32 v45, v0
	v_mov_b32_e32 v46, v0
	v_mov_b32_e32 v47, v0
	v_mov_b32_e32 v48, v0
	v_mov_b32_e32 v49, v0
	v_mov_b32_e32 v50, v0
	v_mov_b32_e32 v51, v0
	v_mov_b32_e32 v52, v0
	v_mov_b32_e32 v53, v0
	v_mov_b32_e32 v54, v0
	v_mov_b32_e32 v55, v0
	v_mov_b32_e32 v56, v0
	v_mov_b32_e32 v57, v0
	v_mov_b32_e32 v58, v0
	v_mov_b32_e32 v59, v0
	v_mov_b32_e32 v60, v0
	v_mov_b32_e32 v61, v0
	v_mov_b32_e32 v62, v0
	v_mov_b32_e32 v63, v0
	v_mov_b32_e32 v64, v0
	v_mov_b32_e32 v65, v0
	v_mov_b32_e32 v66, v0
	v_mov_b32_e32 v67, v0
	v_mov_b32_e32 v68, v0
	v_mov_b32_e32 v69, v0
	v_mov_b32_e32 v70, v0
	v_mov_b32_e32 v71, v0
	v_mov_b32_e32 v72, v0
	v_mov_b32_e32 v73, v0
	v_mov_b32_e32 v74, v0
	v_mov_b32_e32 v75, v0
	v_mov_b32_e32 v76, v0
	v_mov_b32_e32 v77, v0
	v_mov_b32_e32 v78, v0
	v_mov_b32_e32 v79, v0
	v_mov_b32_e32 v80, v0
	v_mov_b32_e32 v81, v0
	v_mov_b32_e32 v82, v0
	v_mov_b32_e32 v83, v0
	v_mov_b32_e32 v84, v0
	v_mov_b32_e32 v85, v0
	v_mov_b32_e32 v86, v0
	v_mov_b32_e32 v87, v0
	v_mov_b32_e32 v88, v0
	v_mov_b32_e32 v89, v0
	v_mov_b32_e32 v90, v0
	v_mov_b32_e32 v91, v0
	v_mov_b32_e32 v92, v0
	v_mov_b32_e32 v93, v0
	v_mov_b32_e32 v94, v0
	v_mov_b32_e32 v95, v0
	v_mov_b32_e32 v96, v0
	v_mov_b32_e32 v97, v0
	v_mov_b32_e32 v98, v0
	v_mov_b32_e32 v99, v0
	v_mov_b32_e32 v100, v0
	v_mov_b32_e32 v101, v0
	v_mov_b32_e32 v102, v0
	v_mov_b32_e32 v103, v0
	v_mov_b32_e32 v104, v0
	v_mov_b32_e32 v105, v0
	v_mov_b32_e32 v106, v0
	v_mov_b32_e32 v107, v0
	v_mov_b32_e32 v108, v0
	v_mov_b32_e32 v109, v0
	v_mov_b32_e32 v110, v0
	v_mov_b32_e32 v111, v0
	v_mov_b32_e32 v112, v0
	v_mov_b32_e32 v113, v0
	v_mov_b32_e32 v114, v0
	v_mov_b32_e32 v115, v0
	v_mov_b32_e32 v116, v0
	v_mov_b32_e32 v117, v0
	v_mov_b32_e32 v118, v0
	v_mov_b32_e32 v119, v0
	v_mov_b32_e32 v120, v0
	v_mov_b32_e32 v121, v0
	v_mov_b32_e32 v122, v0
	v_mov_b32_e32 v123, v0
	v_mov_b32_e32 v124, v0
	v_mov_b32_e32 v125, v0
	v_mov_b32_e32 v126, v0
	v_mov_b32_e32 v127, v0
	s_waitcnt vmcnt(16) lgkmcnt(0)
	s_barrier
	v_readfirstlane_b32 s98, v178
	s_nop 3
	s_lshr_b32 s98, s98, 6
	s_cmp_ge_u32 s98, 4
	s_cbranch_scc1 .Lprio_done_9
	s_setprio 1

.LBB0_2070:
	s_lshr_b32 s4, s3, 1
	s_and_b32 s4, s4, 0x1ffff80
	v_or_b32_e32 v0, s4, v154
	s_and_b32 s3, s3, 0xc0
	v_lshlrev_b32_e32 v139, 7, v0
	v_or_b32_e32 v0, s3, v154
	s_mov_b32 s3, s15
	s_lshl_b64 s[2:3], s[2:3], 16
	s_add_u32 s4, s2, s74
	s_addc_u32 s5, s3, s75
	s_waitcnt vmcnt(16)
	v_lshlrev_b32_e32 v128, 7, v0
	v_lshl_add_u64 v[0:1], s[66:67], 0, v[130:131]
	s_add_u32 s2, s2, s76
	v_lshl_add_u64 v[142:143], v[0:1], 0, s[4:5]
	s_addc_u32 s3, s3, s77
	v_lshl_add_u64 v[0:1], s[66:67], 0, v[134:135]
	v_mov_b32_e32 v72, 0
	v_lshl_add_u64 v[144:145], v[132:133], 0, s[2:3]
	v_lshl_add_u64 v[146:147], v[0:1], 0, s[4:5]
	v_lshl_add_u64 v[148:149], v[136:137], 0, s[2:3]
	s_mov_b32 s4, 0
	s_mov_b64 s[2:3], 0
	v_mov_b32_e32 v73, v72
	v_mov_b32_e32 v74, v72
	v_mov_b32_e32 v75, v72
	v_mov_b32_e32 v88, v72
	v_mov_b32_e32 v89, v72
	v_mov_b32_e32 v90, v72
	v_mov_b32_e32 v91, v72
	v_mov_b32_e32 v0, v72
	v_mov_b32_e32 v1, v72
	v_mov_b32_e32 v2, v72
	v_mov_b32_e32 v3, v72
	v_mov_b32_e32 v4, v72
	v_mov_b32_e32 v5, v72
	v_mov_b32_e32 v6, v72
	v_mov_b32_e32 v7, v72
	v_mov_b32_e32 v8, v72
	v_mov_b32_e32 v9, v72
	v_mov_b32_e32 v10, v72
	v_mov_b32_e32 v11, v72
	v_mov_b32_e32 v12, v72
	v_mov_b32_e32 v13, v72
	v_mov_b32_e32 v14, v72
	v_mov_b32_e32 v15, v72
	v_mov_b32_e32 v16, v72
	v_mov_b32_e32 v17, v72
	v_mov_b32_e32 v18, v72
	v_mov_b32_e32 v19, v72
	v_mov_b32_e32 v20, v72
	v_mov_b32_e32 v21, v72
	v_mov_b32_e32 v22, v72
	v_mov_b32_e32 v23, v72
	v_mov_b32_e32 v24, v72
	v_mov_b32_e32 v25, v72
	v_mov_b32_e32 v26, v72
	v_mov_b32_e32 v27, v72
	v_mov_b32_e32 v28, v72
	v_mov_b32_e32 v29, v72
	v_mov_b32_e32 v30, v72
	v_mov_b32_e32 v31, v72
	v_mov_b32_e32 v32, v72
	v_mov_b32_e32 v33, v72
	v_mov_b32_e32 v34, v72
	v_mov_b32_e32 v35, v72
	v_mov_b32_e32 v36, v72
	v_mov_b32_e32 v37, v72
	v_mov_b32_e32 v38, v72
	v_mov_b32_e32 v39, v72
	v_mov_b32_e32 v40, v72
	v_mov_b32_e32 v41, v72
	v_mov_b32_e32 v42, v72
	v_mov_b32_e32 v43, v72
	v_mov_b32_e32 v44, v72
	v_mov_b32_e32 v45, v72
	v_mov_b32_e32 v46, v72
	v_mov_b32_e32 v47, v72
	v_mov_b32_e32 v48, v72
	v_mov_b32_e32 v49, v72
	v_mov_b32_e32 v50, v72
	v_mov_b32_e32 v51, v72
	v_mov_b32_e32 v52, v72
	v_mov_b32_e32 v53, v72
	v_mov_b32_e32 v54, v72
	v_mov_b32_e32 v55, v72
	v_mov_b32_e32 v56, v72
	v_mov_b32_e32 v57, v72
	v_mov_b32_e32 v58, v72
	v_mov_b32_e32 v59, v72
	v_mov_b32_e32 v60, v72
	v_mov_b32_e32 v61, v72
	v_mov_b32_e32 v62, v72
	v_mov_b32_e32 v63, v72
	v_mov_b32_e32 v64, v72
	v_mov_b32_e32 v65, v72
	v_mov_b32_e32 v66, v72
	v_mov_b32_e32 v67, v72
	v_mov_b32_e32 v68, v72
	v_mov_b32_e32 v69, v72
	v_mov_b32_e32 v70, v72
	v_mov_b32_e32 v71, v72
	v_mov_b32_e32 v76, v72
	v_mov_b32_e32 v77, v72
	v_mov_b32_e32 v78, v72
	v_mov_b32_e32 v79, v72
	v_mov_b32_e32 v80, v72
	v_mov_b32_e32 v81, v72
	v_mov_b32_e32 v82, v72
	v_mov_b32_e32 v83, v72
	v_mov_b32_e32 v84, v72
	v_mov_b32_e32 v85, v72
	v_mov_b32_e32 v86, v72
	v_mov_b32_e32 v87, v72
	v_mov_b32_e32 v92, v72
	v_mov_b32_e32 v93, v72
	v_mov_b32_e32 v94, v72
	v_mov_b32_e32 v95, v72
	v_mov_b32_e32 v96, v72
	v_mov_b32_e32 v97, v72
	v_mov_b32_e32 v98, v72
	v_mov_b32_e32 v99, v72
	v_mov_b32_e32 v100, v72
	v_mov_b32_e32 v101, v72
	v_mov_b32_e32 v102, v72
	v_mov_b32_e32 v103, v72
	v_mov_b32_e32 v104, v72
	v_mov_b32_e32 v105, v72
	v_mov_b32_e32 v106, v72
	v_mov_b32_e32 v107, v72
	v_mov_b32_e32 v108, v72
	v_mov_b32_e32 v109, v72
	v_mov_b32_e32 v110, v72
	v_mov_b32_e32 v111, v72
	v_mov_b32_e32 v112, v72
	v_mov_b32_e32 v113, v72
	v_mov_b32_e32 v114, v72
	v_mov_b32_e32 v115, v72
	v_mov_b32_e32 v116, v72
	v_mov_b32_e32 v117, v72
	v_mov_b32_e32 v118, v72
	v_mov_b32_e32 v119, v72
	v_mov_b32_e32 v120, v72
	v_mov_b32_e32 v121, v72
	v_mov_b32_e32 v122, v72
	v_mov_b32_e32 v123, v72
	v_mov_b32_e32 v124, v72
	v_mov_b32_e32 v125, v72
	v_mov_b32_e32 v126, v72
	v_mov_b32_e32 v127, v72
	s_waitcnt vmcnt(16) lgkmcnt(0)
	s_barrier
	v_readfirstlane_b32 s98, v178
	s_nop 3
	s_lshr_b32 s98, s98, 6
	s_cmp_ge_u32 s98, 4
	s_cbranch_scc1 .Lprio_done_10
	s_setprio 1
